# NSA selected loop: one ds_read_b128 for the 4 tile indices per group; moba_own merge: hoist slot 1/2 partial loads alongside slot 0
# baseline (speedup 1.0000x reference)
; DI float bflo(uint32_t w) { return __uint_as_float(w << 16); }
; DI float bfhi(uint32_t w) { return __uint_as_float(w & 0xffff0000u); }
; DI float fexp2(float x) { return __builtin_amdgcn_exp2f(x); }
; DI void moba_own_item(int ws, PP p, char* shm, int item) {
;     ...
;   const int nsl = qb < 3 ? qb : 3;
; #pragma unroll
;   for (int sl = 0; sl < 3; ++sl) {
;     if (sl >= nsl) break;
;     const u16* pe = p->part + (((long)(b * 8 + h) * SEQ + tq) * 3 + sl) * 72;
;     const float ms = ((const float*)pe)[0], ls = ((const float*)pe)[1];
;     const float mn = fmaxf(m, ms);
;     const float a = fexp2(m - mn), c = fexp2(ms - mn) * ls;
; #pragma unroll
;     for (int db = 0; db < 2; ++db)
; #pragma unroll
;       for (int q = 0; q < 4; ++q) {
;         const u32x2 w = *(const u32x2*)(pe + 8 + db * 32 + 8 * q + 4 * hh);
;         o[db][4 * q] = o[db][4 * q] * a + c * bflo(w[0]);
;         o[db][4 * q + 1] = o[db][4 * q + 1] * a + c * bfhi(w[0]);
;         o[db][4 * q + 2] = o[db][4 * q + 2] * a + c * bflo(w[1]);
;         o[db][4 * q + 3] = o[db][4 * q + 3] * a + c * bfhi(w[1]);
;       }
;     l = l * a + c;
;     m = mn;
;   }
.LBB0_827:
	s_andn2_b64 vcc, exec, s[10:11]
	s_cbranch_vccnz .LBB0_832
	s_load_dwordx2 s[4:5], s[16:17], 0x178
	s_lshl_b32 s20, s3, 13
	v_lshl_add_u64 v[34:35], s[20:21], 0, v[126:127]
	v_lshlrev_b32_e32 v120, 1, v124
	v_max_f32_e32 v36, v99, v99
	s_waitcnt lgkmcnt(0)
	v_mov_b64_e32 v[32:33], s[4:5]
	v_mad_u64_u32 v[32:33], s[4:5], v34, s39, v[32:33]
	v_mad_i32_i24 v33, v35, s39, v33
	global_load_dwordx2 v[38:39], v[32:33], off
	v_lshl_add_u64 v[34:35], v[32:33], 0, v[120:121]
	global_load_dwordx2 v[40:41], v[34:35], off offset:64
	global_load_dwordx2 v[42:43], v[34:35], off offset:128
	global_load_dwordx2 v[44:45], v[34:35], off offset:16
	global_load_dwordx2 v[46:47], v[34:35], off offset:32
	global_load_dwordx2 v[48:49], v[34:35], off offset:48
	global_load_dwordx2 v[50:51], v[34:35], off offset:80
	global_load_dwordx2 v[52:53], v[34:35], off offset:96
	global_load_dwordx2 v[54:55], v[34:35], off offset:112
	global_load_dwordx2 v[196:197], v[32:33], off offset:144
	global_load_dwordx2 v[198:199], v[34:35], off offset:208
	global_load_dwordx2 v[200:201], v[34:35], off offset:272
	global_load_dwordx2 v[202:203], v[34:35], off offset:160
	global_load_dwordx2 v[204:205], v[34:35], off offset:176
	global_load_dwordx2 v[206:207], v[34:35], off offset:192
	global_load_dwordx2 v[208:209], v[34:35], off offset:224
	global_load_dwordx2 v[210:211], v[34:35], off offset:240
	global_load_dwordx2 v[212:213], v[34:35], off offset:256
	global_load_dwordx2 v[216:217], v[32:33], off offset:288
	global_load_dwordx2 v[218:219], v[34:35], off offset:352
	global_load_dwordx2 v[220:221], v[34:35], off offset:416
	global_load_dwordx2 v[222:223], v[34:35], off offset:304
	global_load_dwordx2 v[224:225], v[34:35], off offset:320
	global_load_dwordx2 v[226:227], v[34:35], off offset:336
	global_load_dwordx2 v[228:229], v[34:35], off offset:368
	global_load_dwordx2 v[230:231], v[34:35], off offset:384
	global_load_dwordx2 v[232:233], v[34:35], off offset:400
	v_mov_b32_e32 v58, v15
	v_mov_b32_e32 v56, v31
	s_cmp_eq_u32 s41, 30
	s_waitcnt vmcnt(25)
	v_lshlrev_b32_e32 v66, 16, v40
	v_and_b32_e32 v67, 0xffff0000, v40
	s_waitcnt vmcnt(23)
	v_lshlrev_b32_e32 v60, 16, v44
	v_and_b32_e32 v61, 0xffff0000, v44
	v_lshlrev_b32_e32 v44, 16, v45
	v_max_f32_e32 v15, v38, v38
	v_max_f32_e32 v36, v36, v15
	v_mov_b32_e32 v97, v39
	v_sub_f32_e32 v39, v99, v36
	v_exp_f32_e32 v40, v39
	v_sub_f32_e32 v38, v38, v36
	v_exp_f32_e32 v39, v38
	v_and_b32_e32 v45, 0xffff0000, v45
	v_mov_b32_e32 v38, v40
	v_lshlrev_b32_e32 v31, 16, v41
	v_pk_mul_f32 v[76:77], v[96:97], v[38:39]
	v_and_b32_e32 v41, 0xffff0000, v41
	v_and_b32_e32 v15, 0xffff0000, v43
	v_lshlrev_b32_e32 v74, 16, v42
	v_and_b32_e32 v75, 0xffff0000, v42
	v_mul_f32_e32 v42, v14, v40
	v_mov_b32_e32 v14, v40
	v_pk_mul_f32 v[44:45], v[76:77], v[44:45] op_sel:[1,0]
	v_mov_b32_e32 v57, v77
	v_mov_b32_e32 v59, v77
	v_lshlrev_b32_e32 v37, 16, v43
	s_waitcnt vmcnt(22)
	v_lshlrev_b32_e32 v62, 16, v46
	v_and_b32_e32 v63, 0xffff0000, v46
	v_lshlrev_b32_e32 v46, 16, v47
	v_and_b32_e32 v47, 0xffff0000, v47
	s_waitcnt vmcnt(21)
	v_lshlrev_b32_e32 v64, 16, v48
	v_and_b32_e32 v65, 0xffff0000, v48
	v_lshlrev_b32_e32 v48, 16, v49
	v_and_b32_e32 v49, 0xffff0000, v49
	s_waitcnt vmcnt(20)
	v_lshlrev_b32_e32 v68, 16, v50
	v_and_b32_e32 v69, 0xffff0000, v50
	v_lshlrev_b32_e32 v50, 16, v51
	v_and_b32_e32 v51, 0xffff0000, v51
	s_waitcnt vmcnt(19)
	v_lshlrev_b32_e32 v70, 16, v52
	v_and_b32_e32 v71, 0xffff0000, v52
	v_lshlrev_b32_e32 v52, 16, v53
	v_and_b32_e32 v53, 0xffff0000, v53
	s_waitcnt vmcnt(18)
	v_lshlrev_b32_e32 v72, 16, v54
	v_and_b32_e32 v73, 0xffff0000, v54
	v_lshlrev_b32_e32 v54, 16, v55
	v_and_b32_e32 v55, 0xffff0000, v55
	v_pk_fma_f32 v[18:19], v[18:19], v[40:41], v[44:45] op_sel_hi:[1,0,1]
	v_pk_mul_f32 v[44:45], v[56:57], v[40:41]
	v_pk_mul_f32 v[14:15], v[58:59], v[14:15]
	v_mul_f32_e32 v30, v30, v40
	v_pk_mul_f32 v[60:61], v[76:77], v[60:61] op_sel:[1,0]
	v_pk_mul_f32 v[62:63], v[76:77], v[62:63] op_sel:[1,0]
	v_pk_mul_f32 v[46:47], v[76:77], v[46:47] op_sel:[1,0]
	v_pk_mul_f32 v[64:65], v[76:77], v[64:65] op_sel:[1,0]
	v_pk_mul_f32 v[48:49], v[76:77], v[48:49] op_sel:[1,0]
	v_pk_mul_f32 v[66:67], v[76:77], v[66:67] op_sel:[1,0]
	v_mul_f32_e32 v78, v77, v31
	v_pk_mul_f32 v[68:69], v[76:77], v[68:69] op_sel:[1,0]
	v_pk_mul_f32 v[50:51], v[76:77], v[50:51] op_sel:[1,0]
	v_pk_mul_f32 v[70:71], v[76:77], v[70:71] op_sel:[1,0]
	v_pk_mul_f32 v[52:53], v[76:77], v[52:53] op_sel:[1,0]
	v_pk_mul_f32 v[72:73], v[76:77], v[72:73] op_sel:[1,0]
	v_pk_mul_f32 v[54:55], v[76:77], v[54:55] op_sel:[1,0]
	v_pk_mul_f32 v[74:75], v[76:77], v[74:75] op_sel:[1,0]
	v_mul_f32_e32 v80, v77, v37
	v_mov_b32_e32 v31, v44
	v_mov_b32_e32 v79, v45
	v_mov_b32_e32 v43, v14
	v_mov_b32_e32 v81, v15
	v_pk_fma_f32 v[16:17], v[16:17], v[40:41], v[60:61] op_sel_hi:[1,0,1]
	v_pk_fma_f32 v[20:21], v[20:21], v[40:41], v[62:63] op_sel_hi:[1,0,1]
	v_pk_fma_f32 v[22:23], v[22:23], v[40:41], v[46:47] op_sel_hi:[1,0,1]
	v_pk_fma_f32 v[24:25], v[24:25], v[40:41], v[64:65] op_sel_hi:[1,0,1]
	v_pk_fma_f32 v[26:27], v[26:27], v[40:41], v[48:49] op_sel_hi:[1,0,1]
	v_pk_fma_f32 v[28:29], v[28:29], v[40:41], v[66:67] op_sel_hi:[1,0,1]
	v_pk_fma_f32 v[0:1], v[0:1], v[40:41], v[68:69] op_sel_hi:[1,0,1]
	v_pk_fma_f32 v[2:3], v[2:3], v[40:41], v[50:51] op_sel_hi:[1,0,1]
	v_pk_fma_f32 v[4:5], v[4:5], v[40:41], v[70:71] op_sel_hi:[1,0,1]
	v_pk_fma_f32 v[6:7], v[6:7], v[40:41], v[52:53] op_sel_hi:[1,0,1]
	v_pk_fma_f32 v[8:9], v[8:9], v[40:41], v[72:73] op_sel_hi:[1,0,1]
	v_pk_fma_f32 v[10:11], v[10:11], v[40:41], v[54:55] op_sel_hi:[1,0,1]
	v_pk_fma_f32 v[12:13], v[12:13], v[40:41], v[74:75] op_sel_hi:[1,0,1]
	v_pk_add_f32 v[30:31], v[30:31], v[78:79]
	v_pk_add_f32 v[14:15], v[42:43], v[80:81]
	v_pk_fma_f32 v[96:97], v[96:97], v[38:39], v[76:77] op_sel:[0,0,1] op_sel_hi:[1,1,0]
	s_cbranch_scc1 .LBB0_831
; DI float bflo(uint32_t w) { return __uint_as_float(w << 16); }
; DI float bfhi(uint32_t w) { return __uint_as_float(w & 0xffff0000u); }
; DI float fexp2(float x) { return __builtin_amdgcn_exp2f(x); }
; DI void moba_own_item(int ws, PP p, char* shm, int item) {
;     ...
;   for (int sl = 0; sl < 3; ++sl) {
;     if (sl >= nsl) break;
;     const u16* pe = p->part + (((long)(b * 8 + h) * SEQ + tq) * 3 + sl) * 72;
;     const float ms = ((const float*)pe)[0], ls = ((const float*)pe)[1];
;     const float mn = fmaxf(m, ms);
;     const float a = fexp2(m - mn), c = fexp2(ms - mn) * ls;
; #pragma unroll
;     for (int db = 0; db < 2; ++db)
; #pragma unroll
;       for (int q = 0; q < 4; ++q) {
;         const u32x2 w = *(const u32x2*)(pe + 8 + db * 32 + 8 * q + 4 * hh);
;         o[db][4 * q] = o[db][4 * q] * a + c * bflo(w[0]);
;         o[db][4 * q + 1] = o[db][4 * q + 1] * a + c * bfhi(w[0]);
;         o[db][4 * q + 2] = o[db][4 * q + 2] * a + c * bflo(w[1]);
;         o[db][4 * q + 3] = o[db][4 * q + 3] * a + c * bfhi(w[1]);
;       }
;     l = l * a + c;
;     m = mn;
;   }
	s_waitcnt vmcnt(9)
	v_mov_b64_e32 v[38:39], v[196:197]
	v_mov_b64_e32 v[40:41], v[198:199]
	v_mov_b64_e32 v[42:43], v[200:201]
	v_mov_b64_e32 v[44:45], v[202:203]
	v_mov_b64_e32 v[46:47], v[204:205]
	v_mov_b64_e32 v[48:49], v[206:207]
	v_mov_b64_e32 v[50:51], v[208:209]
	v_mov_b64_e32 v[52:53], v[210:211]
	v_mov_b64_e32 v[54:55], v[212:213]
	v_max_f32_e32 v37, v36, v36
	v_mov_b32_e32 v56, v31
	v_mov_b32_e32 v58, v15
	s_cmp_eq_u32 s41, 29
	s_waitcnt vmcnt(8)
	v_max_f32_e32 v31, v38, v38
	v_max_f32_e32 v37, v37, v31
	v_sub_f32_e32 v31, v36, v37
	s_waitcnt vmcnt(7)
	v_lshlrev_b32_e32 v66, 16, v40
	v_and_b32_e32 v67, 0xffff0000, v40
	v_exp_f32_e32 v40, v31
	v_sub_f32_e32 v31, v38, v37
	v_mov_b32_e32 v97, v39
	v_exp_f32_e32 v39, v31
	v_mov_b32_e32 v38, v40
	v_lshlrev_b32_e32 v57, 16, v41
	s_waitcnt vmcnt(6)
	v_lshlrev_b32_e32 v59, 16, v43
	s_waitcnt vmcnt(5)
	v_lshlrev_b32_e32 v60, 16, v44
	v_and_b32_e32 v61, 0xffff0000, v44
	v_lshlrev_b32_e32 v44, 16, v45
	v_and_b32_e32 v45, 0xffff0000, v45
	v_pk_mul_f32 v[76:77], v[96:97], v[38:39]
	v_and_b32_e32 v41, 0xffff0000, v41
	v_and_b32_e32 v15, 0xffff0000, v43
	v_lshlrev_b32_e32 v74, 16, v42
	v_and_b32_e32 v75, 0xffff0000, v42
	v_mul_f32_e32 v42, v14, v40
	v_mov_b32_e32 v14, v40
	v_pk_mul_f32 v[44:45], v[76:77], v[44:45] op_sel:[1,0]
	v_mul_f32_e32 v78, v77, v57
	v_mov_b32_e32 v57, v77
	v_mul_f32_e32 v80, v77, v59
	v_mov_b32_e32 v59, v77
	s_waitcnt vmcnt(4)
	v_lshlrev_b32_e32 v62, 16, v46
	v_and_b32_e32 v63, 0xffff0000, v46
	v_lshlrev_b32_e32 v46, 16, v47
	v_and_b32_e32 v47, 0xffff0000, v47
	s_waitcnt vmcnt(3)
	v_lshlrev_b32_e32 v64, 16, v48
	v_and_b32_e32 v65, 0xffff0000, v48
	v_lshlrev_b32_e32 v48, 16, v49
	v_and_b32_e32 v49, 0xffff0000, v49
	s_waitcnt vmcnt(2)
	v_lshlrev_b32_e32 v68, 16, v50
	v_and_b32_e32 v69, 0xffff0000, v50
	v_lshlrev_b32_e32 v50, 16, v51
	v_and_b32_e32 v51, 0xffff0000, v51
	s_waitcnt vmcnt(1)
	v_lshlrev_b32_e32 v70, 16, v52
	v_and_b32_e32 v71, 0xffff0000, v52
	v_lshlrev_b32_e32 v52, 16, v53
	v_and_b32_e32 v53, 0xffff0000, v53
	s_waitcnt vmcnt(0)
	v_lshlrev_b32_e32 v72, 16, v54
	v_and_b32_e32 v73, 0xffff0000, v54
	v_lshlrev_b32_e32 v54, 16, v55
	v_and_b32_e32 v55, 0xffff0000, v55
	v_pk_fma_f32 v[18:19], v[18:19], v[40:41], v[44:45] op_sel_hi:[1,0,1]
	v_pk_mul_f32 v[44:45], v[56:57], v[40:41]
	v_pk_mul_f32 v[14:15], v[58:59], v[14:15]
	v_mul_f32_e32 v30, v30, v40
	v_pk_mul_f32 v[60:61], v[76:77], v[60:61] op_sel:[1,0]
	v_pk_mul_f32 v[62:63], v[76:77], v[62:63] op_sel:[1,0]
	v_pk_mul_f32 v[46:47], v[76:77], v[46:47] op_sel:[1,0]
	v_pk_mul_f32 v[64:65], v[76:77], v[64:65] op_sel:[1,0]
	v_pk_mul_f32 v[48:49], v[76:77], v[48:49] op_sel:[1,0]
	v_pk_mul_f32 v[66:67], v[76:77], v[66:67] op_sel:[1,0]
	v_pk_mul_f32 v[68:69], v[76:77], v[68:69] op_sel:[1,0]
	v_pk_mul_f32 v[50:51], v[76:77], v[50:51] op_sel:[1,0]
	v_pk_mul_f32 v[70:71], v[76:77], v[70:71] op_sel:[1,0]
	v_pk_mul_f32 v[52:53], v[76:77], v[52:53] op_sel:[1,0]
	v_pk_mul_f32 v[72:73], v[76:77], v[72:73] op_sel:[1,0]
	v_pk_mul_f32 v[54:55], v[76:77], v[54:55] op_sel:[1,0]
	v_pk_mul_f32 v[74:75], v[76:77], v[74:75] op_sel:[1,0]
	v_mov_b32_e32 v31, v44
	v_mov_b32_e32 v79, v45
	v_mov_b32_e32 v43, v14
	v_mov_b32_e32 v81, v15
	v_pk_fma_f32 v[16:17], v[16:17], v[40:41], v[60:61] op_sel_hi:[1,0,1]
	v_pk_fma_f32 v[20:21], v[20:21], v[40:41], v[62:63] op_sel_hi:[1,0,1]
	v_pk_fma_f32 v[22:23], v[22:23], v[40:41], v[46:47] op_sel_hi:[1,0,1]
	v_pk_fma_f32 v[24:25], v[24:25], v[40:41], v[64:65] op_sel_hi:[1,0,1]
	v_pk_fma_f32 v[26:27], v[26:27], v[40:41], v[48:49] op_sel_hi:[1,0,1]
	v_pk_fma_f32 v[28:29], v[28:29], v[40:41], v[66:67] op_sel_hi:[1,0,1]
	v_pk_fma_f32 v[0:1], v[0:1], v[40:41], v[68:69] op_sel_hi:[1,0,1]
	v_pk_fma_f32 v[2:3], v[2:3], v[40:41], v[50:51] op_sel_hi:[1,0,1]
	v_pk_fma_f32 v[4:5], v[4:5], v[40:41], v[70:71] op_sel_hi:[1,0,1]
	v_pk_fma_f32 v[6:7], v[6:7], v[40:41], v[52:53] op_sel_hi:[1,0,1]
	v_pk_fma_f32 v[8:9], v[8:9], v[40:41], v[72:73] op_sel_hi:[1,0,1]
	v_pk_fma_f32 v[10:11], v[10:11], v[40:41], v[54:55] op_sel_hi:[1,0,1]
	v_pk_fma_f32 v[12:13], v[12:13], v[40:41], v[74:75] op_sel_hi:[1,0,1]
	v_pk_add_f32 v[30:31], v[30:31], v[78:79]
	v_pk_add_f32 v[14:15], v[42:43], v[80:81]
	v_pk_fma_f32 v[96:97], v[96:97], v[38:39], v[76:77] op_sel:[0,0,1] op_sel_hi:[1,1,0]
	s_cbranch_scc1 .LBB0_831
; DI float bflo(uint32_t w) { return __uint_as_float(w << 16); }
; DI float bfhi(uint32_t w) { return __uint_as_float(w & 0xffff0000u); }
; DI float fexp2(float x) { return __builtin_amdgcn_exp2f(x); }
; DI void moba_own_item(int ws, PP p, char* shm, int item) {
;     ...
;   const int nsl = qb < 3 ? qb : 3;
; #pragma unroll
;   for (int sl = 0; sl < 3; ++sl) {
;     if (sl >= nsl) break;
;     const u16* pe = p->part + (((long)(b * 8 + h) * SEQ + tq) * 3 + sl) * 72;
;     const float ms = ((const float*)pe)[0], ls = ((const float*)pe)[1];
;     const float mn = fmaxf(m, ms);
;     const float a = fexp2(m - mn), c = fexp2(ms - mn) * ls;
; #pragma unroll
;     for (int db = 0; db < 2; ++db)
; #pragma unroll
;       for (int q = 0; q < 4; ++q) {
;         const u32x2 w = *(const u32x2*)(pe + 8 + db * 32 + 8 * q + 4 * hh);
;         o[db][4 * q] = o[db][4 * q] * a + c * bflo(w[0]);
;         o[db][4 * q + 1] = o[db][4 * q + 1] * a + c * bfhi(w[0]);
;         o[db][4 * q + 2] = o[db][4 * q + 2] * a + c * bflo(w[1]);
;         o[db][4 * q + 3] = o[db][4 * q + 3] * a + c * bfhi(w[1]);
;       }
;     l = l * a + c;
;     m = mn;
;   }
	s_waitcnt vmcnt(0)
	v_mov_b64_e32 v[38:39], v[216:217]
	v_mov_b64_e32 v[40:41], v[218:219]
	v_mov_b64_e32 v[42:43], v[220:221]
	v_mov_b64_e32 v[44:45], v[222:223]
	v_mov_b64_e32 v[46:47], v[224:225]
	v_mov_b64_e32 v[48:49], v[226:227]
	v_mov_b64_e32 v[50:51], v[228:229]
	v_mov_b64_e32 v[52:53], v[230:231]
	v_mov_b64_e32 v[54:55], v[232:233]
	v_max_f32_e32 v33, v37, v37
	v_mov_b32_e32 v32, v31
	v_mov_b32_e32 v34, v15
	s_waitcnt vmcnt(8)
	v_max_f32_e32 v31, v38, v38
	v_max_f32_e32 v31, v33, v31
	v_sub_f32_e32 v33, v37, v31
	s_waitcnt vmcnt(7)
	v_lshlrev_b32_e32 v62, 16, v40
	v_and_b32_e32 v63, 0xffff0000, v40
	v_exp_f32_e32 v40, v33
	v_sub_f32_e32 v31, v38, v31
	v_exp_f32_e32 v31, v31
	v_mov_b32_e32 v97, v39
	v_mul_f32_e32 v38, v30, v40
	v_mov_b32_e32 v30, v40
	v_lshlrev_b32_e32 v35, 16, v41
	s_waitcnt vmcnt(5)
	v_lshlrev_b32_e32 v56, 16, v44
	v_and_b32_e32 v57, 0xffff0000, v44
	s_waitcnt vmcnt(4)
	v_lshlrev_b32_e32 v58, 16, v46
	v_and_b32_e32 v59, 0xffff0000, v46
	s_waitcnt vmcnt(3)
	v_lshlrev_b32_e32 v60, 16, v48
	v_and_b32_e32 v61, 0xffff0000, v48
	v_pk_mul_f32 v[70:71], v[96:97], v[30:31]
	v_and_b32_e32 v41, 0xffff0000, v41
	v_and_b32_e32 v15, 0xffff0000, v43
	v_lshlrev_b32_e32 v36, 16, v42
	v_and_b32_e32 v37, 0xffff0000, v42
	v_mul_f32_e32 v42, v14, v40
	v_mov_b32_e32 v14, v40
	v_pk_mul_f32 v[30:31], v[70:71], v[56:57] op_sel:[1,0]
	v_pk_mul_f32 v[56:57], v[70:71], v[58:59] op_sel:[1,0]
	v_pk_mul_f32 v[58:59], v[70:71], v[60:61] op_sel:[1,0]
	v_pk_mul_f32 v[60:61], v[70:71], v[62:63] op_sel:[1,0]
	v_mul_f32_e32 v62, v71, v35
	v_mov_b32_e32 v33, v71
	v_mov_b32_e32 v35, v71
	v_lshlrev_b32_e32 v72, 16, v43
	v_lshlrev_b32_e32 v44, 16, v45
	v_and_b32_e32 v45, 0xffff0000, v45
	v_lshlrev_b32_e32 v46, 16, v47
	v_and_b32_e32 v47, 0xffff0000, v47
	v_lshlrev_b32_e32 v48, 16, v49
	v_and_b32_e32 v49, 0xffff0000, v49
	s_waitcnt vmcnt(2)
	v_lshlrev_b32_e32 v64, 16, v50
	v_and_b32_e32 v65, 0xffff0000, v50
	v_lshlrev_b32_e32 v50, 16, v51
	v_and_b32_e32 v51, 0xffff0000, v51
	s_waitcnt vmcnt(1)
	v_lshlrev_b32_e32 v66, 16, v52
	v_and_b32_e32 v67, 0xffff0000, v52
	v_lshlrev_b32_e32 v52, 16, v53
	v_and_b32_e32 v53, 0xffff0000, v53
	s_waitcnt vmcnt(0)
	v_lshlrev_b32_e32 v68, 16, v54
	v_and_b32_e32 v69, 0xffff0000, v54
	v_lshlrev_b32_e32 v54, 16, v55
	v_and_b32_e32 v55, 0xffff0000, v55
	v_pk_mul_f32 v[32:33], v[32:33], v[40:41]
	v_pk_mul_f32 v[14:15], v[34:35], v[14:15]
	v_pk_mul_f32 v[44:45], v[70:71], v[44:45] op_sel:[1,0]
	v_pk_mul_f32 v[46:47], v[70:71], v[46:47] op_sel:[1,0]
	v_pk_mul_f32 v[48:49], v[70:71], v[48:49] op_sel:[1,0]
	v_pk_mul_f32 v[64:65], v[70:71], v[64:65] op_sel:[1,0]
	v_pk_mul_f32 v[50:51], v[70:71], v[50:51] op_sel:[1,0]
	v_pk_mul_f32 v[66:67], v[70:71], v[66:67] op_sel:[1,0]
	v_pk_mul_f32 v[52:53], v[70:71], v[52:53] op_sel:[1,0]
	v_pk_mul_f32 v[68:69], v[70:71], v[68:69] op_sel:[1,0]
	v_pk_mul_f32 v[54:55], v[70:71], v[54:55] op_sel:[1,0]
	v_pk_mul_f32 v[36:37], v[70:71], v[36:37] op_sel:[1,0]
	v_mul_f32_e32 v72, v71, v72
	v_mov_b32_e32 v39, v32
	v_mov_b32_e32 v63, v33
	v_mov_b32_e32 v43, v14
	v_mov_b32_e32 v73, v15
	v_pk_fma_f32 v[16:17], v[16:17], v[40:41], v[30:31] op_sel_hi:[1,0,1]
	v_pk_fma_f32 v[18:19], v[18:19], v[40:41], v[44:45] op_sel_hi:[1,0,1]
	v_pk_fma_f32 v[20:21], v[20:21], v[40:41], v[56:57] op_sel_hi:[1,0,1]
	v_pk_fma_f32 v[22:23], v[22:23], v[40:41], v[46:47] op_sel_hi:[1,0,1]
	v_pk_fma_f32 v[24:25], v[24:25], v[40:41], v[58:59] op_sel_hi:[1,0,1]
	v_pk_fma_f32 v[26:27], v[26:27], v[40:41], v[48:49] op_sel_hi:[1,0,1]
	v_pk_fma_f32 v[28:29], v[28:29], v[40:41], v[60:61] op_sel_hi:[1,0,1]
	v_pk_fma_f32 v[0:1], v[0:1], v[40:41], v[64:65] op_sel_hi:[1,0,1]
	v_pk_fma_f32 v[2:3], v[2:3], v[40:41], v[50:51] op_sel_hi:[1,0,1]
	v_pk_fma_f32 v[4:5], v[4:5], v[40:41], v[66:67] op_sel_hi:[1,0,1]
	v_pk_fma_f32 v[6:7], v[6:7], v[40:41], v[52:53] op_sel_hi:[1,0,1]
	v_pk_fma_f32 v[8:9], v[8:9], v[40:41], v[68:69] op_sel_hi:[1,0,1]
	v_pk_add_f32 v[30:31], v[38:39], v[62:63]
	v_pk_fma_f32 v[10:11], v[10:11], v[40:41], v[54:55] op_sel_hi:[1,0,1]
	v_pk_fma_f32 v[12:13], v[12:13], v[40:41], v[36:37] op_sel_hi:[1,0,1]
	v_pk_add_f32 v[14:15], v[42:43], v[72:73]
	v_add_f32_e32 v96, v70, v71

; DI void nsa_item(int ws, PP p, char* shm, int item) {
;     ...
;       auto issue = [&](int g4) {
; #pragma unroll
;         for (int t = 0; t < 4; ++t) {
;           const int idx = g4 * 4 + t;
;           if (idx < ntl) {
;             const int j = tl[idx];
;             kr[t] = *(const u32x4*)(kb_ + ((long)j * 64 + row) * IN1P + seg * 8);
;             vr[t] = *(const u32x4*)(vb_ + (long)row * SEQ + j * 64 + seg * 8);
;           }
;         }
;     ...
;       for (int g4 = 0; g4 < ng; ++g4) {
;         if (g4 + 1 < ng) issue(g4 + 1);
.LBB0_1668:
	v_mov_b32_e32 v232, s27
	ds_read_b128 v[232:235], v232
	s_add_i32 s26, s26, 1
	s_cmp_ge_i32 s26, s25
	s_cselect_b64 s[18:19], -1, 0
	s_and_b64 vcc, exec, s[18:19]
	s_cbranch_vccnz .LBB0_1677
	s_add_i32 s3, s28, 1
	s_cmp_ge_i32 s3, s24
	s_cbranch_scc1 .LBB0_1673
	s_waitcnt vmcnt(1)
	v_mov_b32_e32 v10, s27
	ds_read_b32 v10, v10 offset:16
	s_waitcnt lgkmcnt(0)
	v_ashrrev_i32_e32 v11, 31, v10
	v_lshlrev_b32_e32 v12, 6, v10
	v_lshlrev_b64 v[10:11], 18, v[10:11]
	v_ashrrev_i32_e32 v13, 31, v12
	v_lshl_add_u64 v[10:11], v[198:199], 0, v[10:11]
	v_lshl_add_u64 v[80:81], v[12:13], 1, v[200:201]
	global_load_dwordx4 v[10:13], v[10:11], off offset:2560
	s_nop 0
	global_load_dwordx4 v[144:147], v[80:81], off
	s_add_i32 s3, s28, 2
	s_cmp_ge_i32 s3, s24
	s_cbranch_scc0 .LBB0_1674

; DI uint32_t range_mask(int kpos0, int lo, int hi, int hh) {
;   if (kpos0 >= lo && kpos0 + 63 <= hi) return 0xffffffffu;
;   if (kpos0 > hi || kpos0 + 63 < lo) return 0u;
;   uint32_t vm = 0;
; #pragma unroll
;   for (int kb = 0; kb < 2; ++kb)
; #pragma unroll
;     for (int i = 0; i < 16; ++i) {
;       int kp = kpos0 + kb * 32 + hh * 4 + (i & 3) + 8 * (i >> 2);
;       vm |= (kp >= lo && kp <= hi) ? (1u << (kb * 16 + i)) : 0u;
;     }
;   return vm;
; }
; DI void nsa_item(int ws, PP p, char* shm, int item) {
;     ...
;     auto body = [&](int i, const u16* Ks, const u16* Vs) {
;       const int j = tl[i];
;       const uint32_t w = j < 32 ? ms[0] : j < 64 ? ms[1] : j < 96 ? ms[2] : ms[3];
;       uint32_t vm = ((w >> (j & 31)) & 1u) ? range_mask(j * 64, 0, tok, hh) : 0u;
.LBB0_1677:
	s_add_i32 s3, s28, -3
	s_and_b32 s29, s3, 4
	s_cmp_ge_i32 s3, s24
	s_cbranch_scc1 .LBB0_1694
	v_mov_b32_e32 v96, 0
	s_waitcnt lgkmcnt(0)
	v_mov_b32_e32 v80, v232
	v_cmp_gt_u32_e32 vcc, s75, v80
	s_nop 1
	v_cndmask_b32_e32 v81, v9, v8, vcc
	v_cmp_gt_u32_e32 vcc, 64, v80
	v_readfirstlane_b32 s4, v80
	s_nop 0
	v_cndmask_b32_e32 v81, v81, v7, vcc
	v_cmp_gt_i32_e32 vcc, 32, v80
	s_nop 1
	v_cndmask_b32_e32 v81, v81, v6, vcc
	v_lshrrev_b32_e32 v80, v80, v81
	v_and_b32_e32 v80, 1, v80
	v_cmp_eq_u32_e32 vcc, 1, v80
	s_and_saveexec_b64 s[12:13], vcc
	s_cbranch_execz .LBB0_1684
	s_lshl_b32 s3, s4, 6
	s_cmp_lt_i32 s4, 0
	s_cselect_b64 s[10:11], -1, 0
	s_or_b32 s4, s3, 63
	v_cmp_gt_i32_e32 vcc, s4, v192
	s_or_b64 s[4:5], s[10:11], vcc
	v_mov_b32_e32 v96, -1
	s_and_saveexec_b64 s[20:21], s[4:5]
	s_cbranch_execz .LBB0_1683
	v_cmp_le_i32_e32 vcc, s3, v192
	s_xor_b64 s[4:5], s[10:11], -1
	s_and_b64 s[4:5], s[4:5], vcc
	v_mov_b32_e32 v96, 0
	s_and_saveexec_b64 s[22:23], s[4:5]
	s_cbranch_execz .LBB0_1682
	v_or_b32_e32 v80, s3, v193
	v_cmp_le_i32_e32 vcc, v80, v192
	v_or_b32_e32 v83, 3, v80
	v_or_b32_e32 v84, 10, v80
	v_cndmask_b32_e64 v81, 0, 1, vcc
	v_cmp_lt_i32_e32 vcc, v80, v192
	v_or_b32_e32 v85, 11, v80
	v_or_b32_e32 v86, 16, v80
	v_cndmask_b32_e64 v82, 0, 2, vcc
	v_or_b32_e32 v81, v82, v81
	v_or_b32_e32 v82, 2, v80
	v_cmp_gt_i32_e32 vcc, v82, v192
	v_or_b32_e32 v87, 17, v80
	v_or_b32_e32 v88, 18, v80
	v_cndmask_b32_e64 v82, 4, 0, vcc
	v_cmp_gt_i32_e32 vcc, v83, v192
	v_or_b32_e32 v89, 19, v80
	v_or_b32_e32 v90, 24, v80
	v_cndmask_b32_e64 v83, 8, 0, vcc
	v_or3_b32 v81, v81, v82, v83
	v_or_b32_e32 v82, 8, v80
	v_cmp_gt_i32_e32 vcc, -8, v80
	v_cmp_gt_i32_e64 s[10:11], v82, v192
	v_or_b32_e32 v83, 9, v80
	s_or_b64 s[4:5], vcc, s[10:11]
	v_cmp_gt_i32_e32 vcc, -9, v80
	v_cmp_gt_i32_e64 s[10:11], v83, v192
	v_cndmask_b32_e64 v82, 16, 0, s[4:5]
	s_or_b64 s[4:5], vcc, s[10:11]
	v_cmp_gt_i32_e32 vcc, -10, v80
	v_cmp_gt_i32_e64 s[10:11], v84, v192
	v_cndmask_b32_e64 v83, 32, 0, s[4:5]
	s_or_b64 s[4:5], vcc, s[10:11]
	v_cmp_gt_i32_e32 vcc, -11, v80
	v_cmp_gt_i32_e64 s[10:11], v85, v192
	v_cndmask_b32_e64 v84, 64, 0, s[4:5]
	s_or_b64 s[4:5], vcc, s[10:11]
	v_cmp_gt_i32_e32 vcc, -16, v80
	v_cmp_gt_i32_e64 s[10:11], v86, v192
	v_cndmask_b32_e64 v85, v205, 0, s[4:5]
	s_or_b64 s[4:5], vcc, s[10:11]
	v_cmp_gt_i32_e32 vcc, s76, v80
	v_cmp_gt_i32_e64 s[10:11], v87, v192
	v_cndmask_b32_e64 v86, v206, 0, s[4:5]
	s_or_b64 s[4:5], vcc, s[10:11]
	v_cmp_gt_i32_e32 vcc, s6, v80
	v_cmp_gt_i32_e64 s[10:11], v88, v192
	v_cndmask_b32_e64 v87, v207, 0, s[4:5]
	s_or_b64 s[4:5], vcc, s[10:11]
	v_cmp_gt_i32_e32 vcc, s7, v80
	v_cmp_gt_i32_e64 s[10:11], v89, v192
	v_cndmask_b32_e64 v88, v208, 0, s[4:5]
	s_or_b64 s[4:5], vcc, s[10:11]
	v_cmp_gt_i32_e32 vcc, s82, v80
	v_cmp_gt_i32_e64 s[10:11], v90, v192
	v_or_b32_e32 v91, 25, v80
	v_cndmask_b32_e64 v89, v209, 0, s[4:5]
	s_or_b64 s[4:5], vcc, s[10:11]
	v_cmp_gt_i32_e32 vcc, s83, v80
	v_cmp_gt_i32_e64 s[10:11], v91, v192
	v_or_b32_e32 v92, 26, v80
	v_cndmask_b32_e64 v90, v210, 0, s[4:5]
	s_or_b64 s[4:5], vcc, s[10:11]
	v_cmp_gt_i32_e32 vcc, s96, v80
	v_cmp_gt_i32_e64 s[10:11], v92, v192
	v_or_b32_e32 v93, 27, v80
	v_cndmask_b32_e64 v91, v211, 0, s[4:5]
	s_or_b64 s[4:5], vcc, s[10:11]
	v_cmp_gt_i32_e32 vcc, s8, v80
	v_cmp_gt_i32_e64 s[10:11], v93, v192
	v_or_b32_e32 v94, 32, v80
	v_cndmask_b32_e64 v92, v212, 0, s[4:5]
	s_or_b64 s[4:5], vcc, s[10:11]
	v_cmp_gt_i32_e32 vcc, v94, v192
	v_or_b32_e32 v95, 33, v80
	v_or_b32_e32 v96, 34, v80
	v_cndmask_b32_e64 v94, v214, 0, vcc
	v_cmp_gt_i32_e32 vcc, v95, v192
	v_or_b32_e32 v97, 35, v80
	v_or_b32_e32 v98, 40, v80
	v_cndmask_b32_e64 v95, v215, 0, vcc
	v_cmp_gt_i32_e32 vcc, v96, v192
	v_or_b32_e32 v99, 41, v80
	v_or_b32_e32 v100, 42, v80
	v_cndmask_b32_e64 v96, v216, 0, vcc
	v_cmp_gt_i32_e32 vcc, v97, v192
	v_or_b32_e32 v101, 43, v80
	v_or_b32_e32 v102, 48, v80
	v_cndmask_b32_e64 v97, v217, 0, vcc
	v_cmp_gt_i32_e32 vcc, v98, v192
	v_or_b32_e32 v103, 49, v80
	v_or_b32_e32 v104, 50, v80
	v_cndmask_b32_e64 v98, v218, 0, vcc
	v_cmp_gt_i32_e32 vcc, v99, v192
	v_or_b32_e32 v105, 51, v80
	v_or3_b32 v81, v81, v94, v95
	v_cndmask_b32_e64 v99, v219, 0, vcc
	v_cmp_gt_i32_e32 vcc, v100, v192
	v_or_b32_e32 v106, 56, v80
	v_or3_b32 v81, v81, v96, v97
	v_cndmask_b32_e64 v100, v220, 0, vcc
	v_cmp_gt_i32_e32 vcc, v101, v192
	v_or_b32_e32 v107, 57, v80
	v_or3_b32 v81, v81, v98, v99
	v_cndmask_b32_e64 v101, v221, 0, vcc
	v_cmp_gt_i32_e32 vcc, v102, v192
	v_or_b32_e32 v108, 58, v80
	v_or3_b32 v81, v81, v100, v101
	v_cndmask_b32_e64 v102, v222, 0, vcc
	v_cmp_gt_i32_e32 vcc, v103, v192
	v_or_b32_e32 v80, 59, v80
	v_cndmask_b32_e64 v93, v213, 0, s[4:5]
	v_cndmask_b32_e64 v103, v223, 0, vcc
	v_cmp_gt_i32_e32 vcc, v104, v192
	v_or3_b32 v81, v81, v102, v103
	s_nop 0
	v_cndmask_b32_e64 v104, v224, 0, vcc
	v_cmp_gt_i32_e32 vcc, v105, v192
	s_nop 1
	v_cndmask_b32_e64 v105, v225, 0, vcc
	v_cmp_gt_i32_e32 vcc, v106, v192
	v_or3_b32 v81, v81, v104, v105
	s_nop 0
	v_cndmask_b32_e64 v106, v226, 0, vcc
	v_cmp_gt_i32_e32 vcc, v107, v192
	s_nop 1
	v_cndmask_b32_e64 v107, v227, 0, vcc
	v_cmp_gt_i32_e32 vcc, v108, v192
	v_or3_b32 v81, v81, v106, v107
	s_nop 0
	v_cndmask_b32_e64 v108, 2.0, 0, vcc
	v_cmp_gt_i32_e32 vcc, v80, v192
	s_nop 1
	v_cndmask_b32_e64 v80, v238, 0, vcc
	v_or3_b32 v80, v81, v108, v80
	v_or3_b32 v80, v80, v82, v83
	v_or3_b32 v80, v80, v84, v85
	v_or3_b32 v80, v80, v86, v87
	v_or3_b32 v80, v80, v88, v89
	v_or3_b32 v80, v80, v90, v91
	v_or3_b32 v96, v80, v92, v93

; DI uint32_t range_mask(int kpos0, int lo, int hi, int hh) {
;   if (kpos0 >= lo && kpos0 + 63 <= hi) return 0xffffffffu;
;   if (kpos0 > hi || kpos0 + 63 < lo) return 0u;
;   uint32_t vm = 0;
; #pragma unroll
;   for (int kb = 0; kb < 2; ++kb)
; #pragma unroll
;     for (int i = 0; i < 16; ++i) {
;       int kp = kpos0 + kb * 32 + hh * 4 + (i & 3) + 8 * (i >> 2);
;       vm |= (kp >= lo && kp <= hi) ? (1u << (kb * 16 + i)) : 0u;
;     }
;   return vm;
; }
; DI void nsa_item(int ws, PP p, char* shm, int item) {
;     ...
;     auto body = [&](int i, const u16* Ks, const u16* Vs) {
;       const int j = tl[i];
;       const uint32_t w = j < 32 ? ms[0] : j < 64 ? ms[1] : j < 96 ? ms[2] : ms[3];
;       uint32_t vm = ((w >> (j & 31)) & 1u) ? range_mask(j * 64, 0, tok, hh) : 0u;
.LBB0_1694:
	s_add_i32 s3, s28, -2
	s_cmp_ge_i32 s3, s24
	s_cbranch_scc1 .LBB0_1711
	v_mov_b32_e32 v96, 0
	s_waitcnt lgkmcnt(0)
	v_mov_b32_e32 v80, v233
	v_cmp_gt_u32_e32 vcc, s75, v80
	s_nop 1
	v_cndmask_b32_e32 v81, v9, v8, vcc
	v_cmp_gt_u32_e32 vcc, 64, v80
	v_readfirstlane_b32 s4, v80
	s_nop 0
	v_cndmask_b32_e32 v81, v81, v7, vcc
	v_cmp_gt_i32_e32 vcc, 32, v80
	s_nop 1
	v_cndmask_b32_e32 v81, v81, v6, vcc
	v_lshrrev_b32_e32 v80, v80, v81
	v_and_b32_e32 v80, 1, v80
	v_cmp_eq_u32_e32 vcc, 1, v80
	s_and_saveexec_b64 s[12:13], vcc
	s_cbranch_execz .LBB0_1701
	s_lshl_b32 s3, s4, 6
	s_cmp_lt_i32 s4, 0
	s_cselect_b64 s[10:11], -1, 0
	s_or_b32 s4, s3, 63
	v_cmp_gt_i32_e32 vcc, s4, v192
	s_or_b64 s[4:5], s[10:11], vcc
	v_mov_b32_e32 v96, -1
	s_and_saveexec_b64 s[20:21], s[4:5]
	s_cbranch_execz .LBB0_1700
	v_cmp_le_i32_e32 vcc, s3, v192
	s_xor_b64 s[4:5], s[10:11], -1
	s_and_b64 s[4:5], s[4:5], vcc
	v_mov_b32_e32 v96, 0
	s_and_saveexec_b64 s[22:23], s[4:5]
	s_cbranch_execz .LBB0_1699
	v_or_b32_e32 v80, s3, v193
	v_cmp_le_i32_e32 vcc, v80, v192
	v_or_b32_e32 v83, 3, v80
	v_or_b32_e32 v84, 10, v80
	v_cndmask_b32_e64 v81, 0, 1, vcc
	v_cmp_lt_i32_e32 vcc, v80, v192
	v_or_b32_e32 v85, 11, v80
	v_or_b32_e32 v86, 16, v80
	v_cndmask_b32_e64 v82, 0, 2, vcc
	v_or_b32_e32 v81, v82, v81
	v_or_b32_e32 v82, 2, v80
	v_cmp_gt_i32_e32 vcc, v82, v192
	v_or_b32_e32 v87, 17, v80
	v_or_b32_e32 v88, 18, v80
	v_cndmask_b32_e64 v82, 4, 0, vcc
	v_cmp_gt_i32_e32 vcc, v83, v192
	v_or_b32_e32 v89, 19, v80
	v_or_b32_e32 v90, 24, v80
	v_cndmask_b32_e64 v83, 8, 0, vcc
	v_or3_b32 v81, v81, v82, v83
	v_or_b32_e32 v82, 8, v80
	v_cmp_gt_i32_e32 vcc, -8, v80
	v_cmp_gt_i32_e64 s[10:11], v82, v192
	v_or_b32_e32 v83, 9, v80
	s_or_b64 s[4:5], vcc, s[10:11]
	v_cmp_gt_i32_e32 vcc, -9, v80
	v_cmp_gt_i32_e64 s[10:11], v83, v192
	v_cndmask_b32_e64 v82, 16, 0, s[4:5]
	s_or_b64 s[4:5], vcc, s[10:11]
	v_cmp_gt_i32_e32 vcc, -10, v80
	v_cmp_gt_i32_e64 s[10:11], v84, v192
	v_cndmask_b32_e64 v83, 32, 0, s[4:5]
	s_or_b64 s[4:5], vcc, s[10:11]
	v_cmp_gt_i32_e32 vcc, -11, v80
	v_cmp_gt_i32_e64 s[10:11], v85, v192
	v_cndmask_b32_e64 v84, 64, 0, s[4:5]
	s_or_b64 s[4:5], vcc, s[10:11]
	v_cmp_gt_i32_e32 vcc, -16, v80
	v_cmp_gt_i32_e64 s[10:11], v86, v192
	v_cndmask_b32_e64 v85, v205, 0, s[4:5]
	s_or_b64 s[4:5], vcc, s[10:11]
	v_cmp_gt_i32_e32 vcc, s76, v80
	v_cmp_gt_i32_e64 s[10:11], v87, v192
	v_cndmask_b32_e64 v86, v206, 0, s[4:5]
	s_or_b64 s[4:5], vcc, s[10:11]
	v_cmp_gt_i32_e32 vcc, s6, v80
	v_cmp_gt_i32_e64 s[10:11], v88, v192
	v_cndmask_b32_e64 v87, v207, 0, s[4:5]
	s_or_b64 s[4:5], vcc, s[10:11]
	v_cmp_gt_i32_e32 vcc, s7, v80
	v_cmp_gt_i32_e64 s[10:11], v89, v192
	v_cndmask_b32_e64 v88, v208, 0, s[4:5]
	s_or_b64 s[4:5], vcc, s[10:11]
	v_cmp_gt_i32_e32 vcc, s82, v80
	v_cmp_gt_i32_e64 s[10:11], v90, v192
	v_or_b32_e32 v91, 25, v80
	v_cndmask_b32_e64 v89, v209, 0, s[4:5]
	s_or_b64 s[4:5], vcc, s[10:11]
	v_cmp_gt_i32_e32 vcc, s83, v80
	v_cmp_gt_i32_e64 s[10:11], v91, v192
	v_or_b32_e32 v92, 26, v80
	v_cndmask_b32_e64 v90, v210, 0, s[4:5]
	s_or_b64 s[4:5], vcc, s[10:11]
	v_cmp_gt_i32_e32 vcc, s96, v80
	v_cmp_gt_i32_e64 s[10:11], v92, v192
	v_or_b32_e32 v93, 27, v80
	v_cndmask_b32_e64 v91, v211, 0, s[4:5]
	s_or_b64 s[4:5], vcc, s[10:11]
	v_cmp_gt_i32_e32 vcc, s8, v80
	v_cmp_gt_i32_e64 s[10:11], v93, v192
	v_or_b32_e32 v94, 32, v80
	v_cndmask_b32_e64 v92, v212, 0, s[4:5]
	s_or_b64 s[4:5], vcc, s[10:11]
	v_cmp_gt_i32_e32 vcc, v94, v192
	v_or_b32_e32 v95, 33, v80
	v_or_b32_e32 v96, 34, v80
	v_cndmask_b32_e64 v94, v214, 0, vcc
	v_cmp_gt_i32_e32 vcc, v95, v192
	v_or_b32_e32 v97, 35, v80
	v_or_b32_e32 v98, 40, v80
	v_cndmask_b32_e64 v95, v215, 0, vcc
	v_cmp_gt_i32_e32 vcc, v96, v192
	v_or_b32_e32 v99, 41, v80
	v_or_b32_e32 v100, 42, v80
	v_cndmask_b32_e64 v96, v216, 0, vcc
	v_cmp_gt_i32_e32 vcc, v97, v192
	v_or_b32_e32 v101, 43, v80
	v_or_b32_e32 v102, 48, v80
	v_cndmask_b32_e64 v97, v217, 0, vcc
	v_cmp_gt_i32_e32 vcc, v98, v192
	v_or_b32_e32 v103, 49, v80
	v_or_b32_e32 v104, 50, v80
	v_cndmask_b32_e64 v98, v218, 0, vcc
	v_cmp_gt_i32_e32 vcc, v99, v192
	v_or_b32_e32 v105, 51, v80
	v_or3_b32 v81, v81, v94, v95
	v_cndmask_b32_e64 v99, v219, 0, vcc
	v_cmp_gt_i32_e32 vcc, v100, v192
	v_or_b32_e32 v106, 56, v80
	v_or3_b32 v81, v81, v96, v97
	v_cndmask_b32_e64 v100, v220, 0, vcc
	v_cmp_gt_i32_e32 vcc, v101, v192
	v_or_b32_e32 v107, 57, v80
	v_or3_b32 v81, v81, v98, v99
	v_cndmask_b32_e64 v101, v221, 0, vcc
	v_cmp_gt_i32_e32 vcc, v102, v192
	v_or_b32_e32 v108, 58, v80
	v_or3_b32 v81, v81, v100, v101
	v_cndmask_b32_e64 v102, v222, 0, vcc
	v_cmp_gt_i32_e32 vcc, v103, v192
	v_or_b32_e32 v80, 59, v80
	v_cndmask_b32_e64 v93, v213, 0, s[4:5]
	v_cndmask_b32_e64 v103, v223, 0, vcc
	v_cmp_gt_i32_e32 vcc, v104, v192
	v_or3_b32 v81, v81, v102, v103
	s_nop 0
	v_cndmask_b32_e64 v104, v224, 0, vcc
	v_cmp_gt_i32_e32 vcc, v105, v192
	s_nop 1
	v_cndmask_b32_e64 v105, v225, 0, vcc
	v_cmp_gt_i32_e32 vcc, v106, v192
	v_or3_b32 v81, v81, v104, v105
	s_nop 0
	v_cndmask_b32_e64 v106, v226, 0, vcc
	v_cmp_gt_i32_e32 vcc, v107, v192
	s_nop 1
	v_cndmask_b32_e64 v107, v227, 0, vcc
	v_cmp_gt_i32_e32 vcc, v108, v192
	v_or3_b32 v81, v81, v106, v107
	s_nop 0
	v_cndmask_b32_e64 v108, 2.0, 0, vcc
	v_cmp_gt_i32_e32 vcc, v80, v192
	s_nop 1
	v_cndmask_b32_e64 v80, v238, 0, vcc
	v_or3_b32 v80, v81, v108, v80
	v_or3_b32 v80, v80, v82, v83
	v_or3_b32 v80, v80, v84, v85
	v_or3_b32 v80, v80, v86, v87
	v_or3_b32 v80, v80, v88, v89
	v_or3_b32 v80, v80, v90, v91
	v_or3_b32 v96, v80, v92, v93

; DI uint32_t range_mask(int kpos0, int lo, int hi, int hh) {
;   if (kpos0 >= lo && kpos0 + 63 <= hi) return 0xffffffffu;
;   if (kpos0 > hi || kpos0 + 63 < lo) return 0u;
;   uint32_t vm = 0;
; #pragma unroll
;   for (int kb = 0; kb < 2; ++kb)
; #pragma unroll
;     for (int i = 0; i < 16; ++i) {
;       int kp = kpos0 + kb * 32 + hh * 4 + (i & 3) + 8 * (i >> 2);
;       vm |= (kp >= lo && kp <= hi) ? (1u << (kb * 16 + i)) : 0u;
;     }
;   return vm;
; }
; DI void nsa_item(int ws, PP p, char* shm, int item) {
;     ...
;     auto body = [&](int i, const u16* Ks, const u16* Vs) {
;       const int j = tl[i];
;       const uint32_t w = j < 32 ? ms[0] : j < 64 ? ms[1] : j < 96 ? ms[2] : ms[3];
;       uint32_t vm = ((w >> (j & 31)) & 1u) ? range_mask(j * 64, 0, tok, hh) : 0u;
.LBB0_1711:
	s_add_i32 s3, s28, -1
	s_cmp_ge_i32 s3, s24
	s_cbranch_scc1 .LBB0_1728
	v_mov_b32_e32 v96, 0
	s_waitcnt lgkmcnt(0)
	v_mov_b32_e32 v80, v234
	v_cmp_gt_u32_e32 vcc, s75, v80
	s_nop 1
	v_cndmask_b32_e32 v81, v9, v8, vcc
	v_cmp_gt_u32_e32 vcc, 64, v80
	v_readfirstlane_b32 s4, v80
	s_nop 0
	v_cndmask_b32_e32 v81, v81, v7, vcc
	v_cmp_gt_i32_e32 vcc, 32, v80
	s_nop 1
	v_cndmask_b32_e32 v81, v81, v6, vcc
	v_lshrrev_b32_e32 v80, v80, v81
	v_and_b32_e32 v80, 1, v80
	v_cmp_eq_u32_e32 vcc, 1, v80
	s_and_saveexec_b64 s[12:13], vcc
	s_cbranch_execz .LBB0_1718
	s_lshl_b32 s3, s4, 6
	s_cmp_lt_i32 s4, 0
	s_cselect_b64 s[10:11], -1, 0
	s_or_b32 s4, s3, 63
	v_cmp_gt_i32_e32 vcc, s4, v192
	s_or_b64 s[4:5], s[10:11], vcc
	v_mov_b32_e32 v96, -1
	s_and_saveexec_b64 s[20:21], s[4:5]
	s_cbranch_execz .LBB0_1717
	v_cmp_le_i32_e32 vcc, s3, v192
	s_xor_b64 s[4:5], s[10:11], -1
	s_and_b64 s[4:5], s[4:5], vcc
	v_mov_b32_e32 v96, 0
	s_and_saveexec_b64 s[22:23], s[4:5]
	s_cbranch_execz .LBB0_1716
	v_or_b32_e32 v80, s3, v193
	v_cmp_le_i32_e32 vcc, v80, v192
	v_or_b32_e32 v83, 3, v80
	v_or_b32_e32 v84, 10, v80
	v_cndmask_b32_e64 v81, 0, 1, vcc
	v_cmp_lt_i32_e32 vcc, v80, v192
	v_or_b32_e32 v85, 11, v80
	v_or_b32_e32 v86, 16, v80
	v_cndmask_b32_e64 v82, 0, 2, vcc
	v_or_b32_e32 v81, v82, v81
	v_or_b32_e32 v82, 2, v80
	v_cmp_gt_i32_e32 vcc, v82, v192
	v_or_b32_e32 v87, 17, v80
	v_or_b32_e32 v88, 18, v80
	v_cndmask_b32_e64 v82, 4, 0, vcc
	v_cmp_gt_i32_e32 vcc, v83, v192
	v_or_b32_e32 v89, 19, v80
	v_or_b32_e32 v90, 24, v80
	v_cndmask_b32_e64 v83, 8, 0, vcc
	v_or3_b32 v81, v81, v82, v83
	v_or_b32_e32 v82, 8, v80
	v_cmp_gt_i32_e32 vcc, -8, v80
	v_cmp_gt_i32_e64 s[10:11], v82, v192
	v_or_b32_e32 v83, 9, v80
	s_or_b64 s[4:5], vcc, s[10:11]
	v_cmp_gt_i32_e32 vcc, -9, v80
	v_cmp_gt_i32_e64 s[10:11], v83, v192
	v_cndmask_b32_e64 v82, 16, 0, s[4:5]
	s_or_b64 s[4:5], vcc, s[10:11]
	v_cmp_gt_i32_e32 vcc, -10, v80
	v_cmp_gt_i32_e64 s[10:11], v84, v192
	v_cndmask_b32_e64 v83, 32, 0, s[4:5]
	s_or_b64 s[4:5], vcc, s[10:11]
	v_cmp_gt_i32_e32 vcc, -11, v80
	v_cmp_gt_i32_e64 s[10:11], v85, v192
	v_cndmask_b32_e64 v84, 64, 0, s[4:5]
	s_or_b64 s[4:5], vcc, s[10:11]
	v_cmp_gt_i32_e32 vcc, -16, v80
	v_cmp_gt_i32_e64 s[10:11], v86, v192
	v_cndmask_b32_e64 v85, v205, 0, s[4:5]
	s_or_b64 s[4:5], vcc, s[10:11]
	v_cmp_gt_i32_e32 vcc, s76, v80
	v_cmp_gt_i32_e64 s[10:11], v87, v192
	v_cndmask_b32_e64 v86, v206, 0, s[4:5]
	s_or_b64 s[4:5], vcc, s[10:11]
	v_cmp_gt_i32_e32 vcc, s6, v80
	v_cmp_gt_i32_e64 s[10:11], v88, v192
	v_cndmask_b32_e64 v87, v207, 0, s[4:5]
	s_or_b64 s[4:5], vcc, s[10:11]
	v_cmp_gt_i32_e32 vcc, s7, v80
	v_cmp_gt_i32_e64 s[10:11], v89, v192
	v_cndmask_b32_e64 v88, v208, 0, s[4:5]
	s_or_b64 s[4:5], vcc, s[10:11]
	v_cmp_gt_i32_e32 vcc, s82, v80
	v_cmp_gt_i32_e64 s[10:11], v90, v192
	v_or_b32_e32 v91, 25, v80
	v_cndmask_b32_e64 v89, v209, 0, s[4:5]
	s_or_b64 s[4:5], vcc, s[10:11]
	v_cmp_gt_i32_e32 vcc, s83, v80
	v_cmp_gt_i32_e64 s[10:11], v91, v192
	v_or_b32_e32 v92, 26, v80
	v_cndmask_b32_e64 v90, v210, 0, s[4:5]
	s_or_b64 s[4:5], vcc, s[10:11]
	v_cmp_gt_i32_e32 vcc, s96, v80
	v_cmp_gt_i32_e64 s[10:11], v92, v192
	v_or_b32_e32 v93, 27, v80
	v_cndmask_b32_e64 v91, v211, 0, s[4:5]
	s_or_b64 s[4:5], vcc, s[10:11]
	v_cmp_gt_i32_e32 vcc, s8, v80
	v_cmp_gt_i32_e64 s[10:11], v93, v192
	v_or_b32_e32 v94, 32, v80
	v_cndmask_b32_e64 v92, v212, 0, s[4:5]
	s_or_b64 s[4:5], vcc, s[10:11]
	v_cmp_gt_i32_e32 vcc, v94, v192
	v_or_b32_e32 v95, 33, v80
	v_or_b32_e32 v96, 34, v80
	v_cndmask_b32_e64 v94, v214, 0, vcc
	v_cmp_gt_i32_e32 vcc, v95, v192
	v_or_b32_e32 v97, 35, v80
	v_or_b32_e32 v98, 40, v80
	v_cndmask_b32_e64 v95, v215, 0, vcc
	v_cmp_gt_i32_e32 vcc, v96, v192
	v_or_b32_e32 v99, 41, v80
	v_or_b32_e32 v100, 42, v80
	v_cndmask_b32_e64 v96, v216, 0, vcc
	v_cmp_gt_i32_e32 vcc, v97, v192
	v_or_b32_e32 v101, 43, v80
	v_or_b32_e32 v102, 48, v80
	v_cndmask_b32_e64 v97, v217, 0, vcc
	v_cmp_gt_i32_e32 vcc, v98, v192
	v_or_b32_e32 v103, 49, v80
	v_or_b32_e32 v104, 50, v80
	v_cndmask_b32_e64 v98, v218, 0, vcc
	v_cmp_gt_i32_e32 vcc, v99, v192
	v_or_b32_e32 v105, 51, v80
	v_or3_b32 v81, v81, v94, v95
	v_cndmask_b32_e64 v99, v219, 0, vcc
	v_cmp_gt_i32_e32 vcc, v100, v192
	v_or_b32_e32 v106, 56, v80
	v_or3_b32 v81, v81, v96, v97
	v_cndmask_b32_e64 v100, v220, 0, vcc
	v_cmp_gt_i32_e32 vcc, v101, v192
	v_or_b32_e32 v107, 57, v80
	v_or3_b32 v81, v81, v98, v99
	v_cndmask_b32_e64 v101, v221, 0, vcc
	v_cmp_gt_i32_e32 vcc, v102, v192
	v_or_b32_e32 v108, 58, v80
	v_or3_b32 v81, v81, v100, v101
	v_cndmask_b32_e64 v102, v222, 0, vcc
	v_cmp_gt_i32_e32 vcc, v103, v192
	v_or_b32_e32 v80, 59, v80
	v_cndmask_b32_e64 v93, v213, 0, s[4:5]
	v_cndmask_b32_e64 v103, v223, 0, vcc
	v_cmp_gt_i32_e32 vcc, v104, v192
	v_or3_b32 v81, v81, v102, v103
	s_nop 0
	v_cndmask_b32_e64 v104, v224, 0, vcc
	v_cmp_gt_i32_e32 vcc, v105, v192
	s_nop 1
	v_cndmask_b32_e64 v105, v225, 0, vcc
	v_cmp_gt_i32_e32 vcc, v106, v192
	v_or3_b32 v81, v81, v104, v105
	s_nop 0
	v_cndmask_b32_e64 v106, v226, 0, vcc
	v_cmp_gt_i32_e32 vcc, v107, v192
	s_nop 1
	v_cndmask_b32_e64 v107, v227, 0, vcc
	v_cmp_gt_i32_e32 vcc, v108, v192
	v_or3_b32 v81, v81, v106, v107
	s_nop 0
	v_cndmask_b32_e64 v108, 2.0, 0, vcc
	v_cmp_gt_i32_e32 vcc, v80, v192
	s_nop 1
	v_cndmask_b32_e64 v80, v238, 0, vcc
	v_or3_b32 v80, v81, v108, v80
	v_or3_b32 v80, v80, v82, v83
	v_or3_b32 v80, v80, v84, v85
	v_or3_b32 v80, v80, v86, v87
	v_or3_b32 v80, v80, v88, v89
	v_or3_b32 v80, v80, v90, v91
	v_or3_b32 v96, v80, v92, v93

; DI uint32_t range_mask(int kpos0, int lo, int hi, int hh) {
;   if (kpos0 >= lo && kpos0 + 63 <= hi) return 0xffffffffu;
;   if (kpos0 > hi || kpos0 + 63 < lo) return 0u;
;   uint32_t vm = 0;
; #pragma unroll
;   for (int kb = 0; kb < 2; ++kb)
; #pragma unroll
;     for (int i = 0; i < 16; ++i) {
;       int kp = kpos0 + kb * 32 + hh * 4 + (i & 3) + 8 * (i >> 2);
;       vm |= (kp >= lo && kp <= hi) ? (1u << (kb * 16 + i)) : 0u;
;     }
;   return vm;
; }
; DI void nsa_item(int ws, PP p, char* shm, int item) {
;     ...
;     auto body = [&](int i, const u16* Ks, const u16* Vs) {
;       const int j = tl[i];
;       const uint32_t w = j < 32 ? ms[0] : j < 64 ? ms[1] : j < 96 ? ms[2] : ms[3];
;       uint32_t vm = ((w >> (j & 31)) & 1u) ? range_mask(j * 64, 0, tok, hh) : 0u;
.LBB0_1728:
	s_cmp_ge_i32 s28, s24
	s_cbranch_scc1 .LBB0_1745
	v_mov_b32_e32 v96, 0
	s_waitcnt lgkmcnt(0)
	v_mov_b32_e32 v80, v235
	v_cmp_gt_u32_e32 vcc, s75, v80
	s_nop 1
	v_cndmask_b32_e32 v81, v9, v8, vcc
	v_cmp_gt_u32_e32 vcc, 64, v80
	v_readfirstlane_b32 s4, v80
	s_nop 0
	v_cndmask_b32_e32 v81, v81, v7, vcc
	v_cmp_gt_i32_e32 vcc, 32, v80
	s_nop 1
	v_cndmask_b32_e32 v81, v81, v6, vcc
	v_lshrrev_b32_e32 v80, v80, v81
	v_and_b32_e32 v80, 1, v80
	v_cmp_eq_u32_e32 vcc, 1, v80
	s_and_saveexec_b64 s[12:13], vcc
	s_cbranch_execz .LBB0_1735
	s_lshl_b32 s3, s4, 6
	s_cmp_lt_i32 s4, 0
	s_cselect_b64 s[10:11], -1, 0
	s_or_b32 s4, s3, 63
	v_cmp_gt_i32_e32 vcc, s4, v192
	s_or_b64 s[4:5], s[10:11], vcc
	v_mov_b32_e32 v96, -1
	s_and_saveexec_b64 s[20:21], s[4:5]
	s_cbranch_execz .LBB0_1734
	v_cmp_le_i32_e32 vcc, s3, v192
	s_xor_b64 s[4:5], s[10:11], -1
	s_and_b64 s[4:5], s[4:5], vcc
	v_mov_b32_e32 v96, 0
	s_and_saveexec_b64 s[22:23], s[4:5]
	s_cbranch_execz .LBB0_1733
	v_or_b32_e32 v80, s3, v193
	v_cmp_le_i32_e32 vcc, v80, v192
	v_or_b32_e32 v83, 3, v80
	v_or_b32_e32 v84, 10, v80
	v_cndmask_b32_e64 v81, 0, 1, vcc
	v_cmp_lt_i32_e32 vcc, v80, v192
	v_or_b32_e32 v85, 11, v80
	v_or_b32_e32 v86, 16, v80
	v_cndmask_b32_e64 v82, 0, 2, vcc
	v_or_b32_e32 v81, v82, v81
	v_or_b32_e32 v82, 2, v80
	v_cmp_gt_i32_e32 vcc, v82, v192
	v_or_b32_e32 v87, 17, v80
	v_or_b32_e32 v88, 18, v80
	v_cndmask_b32_e64 v82, 4, 0, vcc
	v_cmp_gt_i32_e32 vcc, v83, v192
	v_or_b32_e32 v89, 19, v80
	v_or_b32_e32 v90, 24, v80
	v_cndmask_b32_e64 v83, 8, 0, vcc
	v_or3_b32 v81, v81, v82, v83
	v_or_b32_e32 v82, 8, v80
	v_cmp_gt_i32_e32 vcc, -8, v80
	v_cmp_gt_i32_e64 s[10:11], v82, v192
	v_or_b32_e32 v83, 9, v80
	s_or_b64 s[4:5], vcc, s[10:11]
	v_cmp_gt_i32_e32 vcc, -9, v80
	v_cmp_gt_i32_e64 s[10:11], v83, v192
	v_cndmask_b32_e64 v82, 16, 0, s[4:5]
	s_or_b64 s[4:5], vcc, s[10:11]
	v_cmp_gt_i32_e32 vcc, -10, v80
	v_cmp_gt_i32_e64 s[10:11], v84, v192
	v_cndmask_b32_e64 v83, 32, 0, s[4:5]
	s_or_b64 s[4:5], vcc, s[10:11]
	v_cmp_gt_i32_e32 vcc, -11, v80
	v_cmp_gt_i32_e64 s[10:11], v85, v192
	v_cndmask_b32_e64 v84, 64, 0, s[4:5]
	s_or_b64 s[4:5], vcc, s[10:11]
	v_cmp_gt_i32_e32 vcc, -16, v80
	v_cmp_gt_i32_e64 s[10:11], v86, v192
	v_cndmask_b32_e64 v85, v205, 0, s[4:5]
	s_or_b64 s[4:5], vcc, s[10:11]
	v_cmp_gt_i32_e32 vcc, s76, v80
	v_cmp_gt_i32_e64 s[10:11], v87, v192
	v_cndmask_b32_e64 v86, v206, 0, s[4:5]
	s_or_b64 s[4:5], vcc, s[10:11]
	v_cmp_gt_i32_e32 vcc, s6, v80
	v_cmp_gt_i32_e64 s[10:11], v88, v192
	v_cndmask_b32_e64 v87, v207, 0, s[4:5]
	s_or_b64 s[4:5], vcc, s[10:11]
	v_cmp_gt_i32_e32 vcc, s7, v80
	v_cmp_gt_i32_e64 s[10:11], v89, v192
	v_cndmask_b32_e64 v88, v208, 0, s[4:5]
	s_or_b64 s[4:5], vcc, s[10:11]
	v_cmp_gt_i32_e32 vcc, s82, v80
	v_cmp_gt_i32_e64 s[10:11], v90, v192
	v_or_b32_e32 v91, 25, v80
	v_cndmask_b32_e64 v89, v209, 0, s[4:5]
	s_or_b64 s[4:5], vcc, s[10:11]
	v_cmp_gt_i32_e32 vcc, s83, v80
	v_cmp_gt_i32_e64 s[10:11], v91, v192
	v_or_b32_e32 v92, 26, v80
	v_cndmask_b32_e64 v90, v210, 0, s[4:5]
	s_or_b64 s[4:5], vcc, s[10:11]
	v_cmp_gt_i32_e32 vcc, s96, v80
	v_cmp_gt_i32_e64 s[10:11], v92, v192
	v_or_b32_e32 v93, 27, v80
	v_cndmask_b32_e64 v91, v211, 0, s[4:5]
	s_or_b64 s[4:5], vcc, s[10:11]
	v_cmp_gt_i32_e32 vcc, s8, v80
	v_cmp_gt_i32_e64 s[10:11], v93, v192
	v_or_b32_e32 v94, 32, v80
	v_cndmask_b32_e64 v92, v212, 0, s[4:5]
	s_or_b64 s[4:5], vcc, s[10:11]
	v_cmp_gt_i32_e32 vcc, v94, v192
	v_or_b32_e32 v95, 33, v80
	v_or_b32_e32 v96, 34, v80
	v_cndmask_b32_e64 v94, v214, 0, vcc
	v_cmp_gt_i32_e32 vcc, v95, v192
	v_or_b32_e32 v97, 35, v80
	v_or_b32_e32 v98, 40, v80
	v_cndmask_b32_e64 v95, v215, 0, vcc
	v_cmp_gt_i32_e32 vcc, v96, v192
	v_or_b32_e32 v99, 41, v80
	v_or_b32_e32 v100, 42, v80
	v_cndmask_b32_e64 v96, v216, 0, vcc
	v_cmp_gt_i32_e32 vcc, v97, v192
	v_or_b32_e32 v101, 43, v80
	v_or_b32_e32 v102, 48, v80
	v_cndmask_b32_e64 v97, v217, 0, vcc
	v_cmp_gt_i32_e32 vcc, v98, v192
	v_or_b32_e32 v103, 49, v80
	v_or_b32_e32 v104, 50, v80
	v_cndmask_b32_e64 v98, v218, 0, vcc
	v_cmp_gt_i32_e32 vcc, v99, v192
	v_or_b32_e32 v105, 51, v80
	v_or3_b32 v81, v81, v94, v95
	v_cndmask_b32_e64 v99, v219, 0, vcc
	v_cmp_gt_i32_e32 vcc, v100, v192
	v_or_b32_e32 v106, 56, v80
	v_or3_b32 v81, v81, v96, v97
	v_cndmask_b32_e64 v100, v220, 0, vcc
	v_cmp_gt_i32_e32 vcc, v101, v192
	v_or_b32_e32 v107, 57, v80
	v_or3_b32 v81, v81, v98, v99
	v_cndmask_b32_e64 v101, v221, 0, vcc
	v_cmp_gt_i32_e32 vcc, v102, v192
	v_or_b32_e32 v108, 58, v80
	v_or3_b32 v81, v81, v100, v101
	v_cndmask_b32_e64 v102, v222, 0, vcc
	v_cmp_gt_i32_e32 vcc, v103, v192
	v_or_b32_e32 v80, 59, v80
	v_cndmask_b32_e64 v93, v213, 0, s[4:5]
	v_cndmask_b32_e64 v103, v223, 0, vcc
	v_cmp_gt_i32_e32 vcc, v104, v192
	v_or3_b32 v81, v81, v102, v103
	s_nop 0
	v_cndmask_b32_e64 v104, v224, 0, vcc
	v_cmp_gt_i32_e32 vcc, v105, v192
	s_nop 1
	v_cndmask_b32_e64 v105, v225, 0, vcc
	v_cmp_gt_i32_e32 vcc, v106, v192
	v_or3_b32 v81, v81, v104, v105
	s_nop 0
	v_cndmask_b32_e64 v106, v226, 0, vcc
	v_cmp_gt_i32_e32 vcc, v107, v192
	s_nop 1
	v_cndmask_b32_e64 v107, v227, 0, vcc
	v_cmp_gt_i32_e32 vcc, v108, v192
	v_or3_b32 v81, v81, v106, v107
	s_nop 0
	v_cndmask_b32_e64 v108, 2.0, 0, vcc
	v_cmp_gt_i32_e32 vcc, v80, v192
	s_nop 1
	v_cndmask_b32_e64 v80, v238, 0, vcc
	v_or3_b32 v80, v81, v108, v80
	v_or3_b32 v80, v80, v82, v83
	v_or3_b32 v80, v80, v84, v85
	v_or3_b32 v80, v80, v86, v87
	v_or3_b32 v80, v80, v88, v89
	v_or3_b32 v80, v80, v90, v91
	v_or3_b32 v96, v80, v92, v93

; template <class TF, class BODY>
; DI void kv_loop(u16* kvb, int ntiles, int tid, TF tf, BODY body) {
;     ...
;   __syncthreads();
;   if (ntiles > 0) {
;     tf(0, kp, ldk, vp, ldv);
;     kv_issue(r, kp, ldk, vp, ldv, tid);
;     kv_write(r, kvb, kvb + KVT, tid);
;   }
;   __syncthreads();
; DI void nsa_item(int ws, PP p, char* shm, int item) {
;     ...
;     const int jlo = (t0 > 511 ? t0 - 511 : 0) >> 6, jhi = (t0 + 31) >> 6;
;     const u16* kb_ = u + (long)b * SEQ * IN1P + 1536 + g * 64;
;     const u16* vb_ = p->vt + (long)(8 + bg) * 64 * SEQ;
;     auto tf = [&](int i, const u16*& kp, long& ldk, const u16*& vp, long& ldv) {
;       const int j = jlo + i;
;       kp = kb_ + (long)j * 64 * IN1P; ldk = IN1P;
;       vp = vb_ + j * 64; ldv = SEQ;
;     };
.LBB0_1769:
	s_sub_i32 s3, 0x1de0, s94
	s_ashr_i32 s3, s3, 6
	s_cmpk_gt_i32 s95, 0x1ff
	s_cselect_b32 s18, s3, 0
	s_lshr_b32 s3, s95, 6
	s_lshl_b32 s0, s0, 20
	s_add_u32 s0, s16, s0
	s_addc_u32 s4, s17, 0
	s_add_u32 s10, s0, 0x800000
	s_addc_u32 s11, s4, 0
	s_sub_i32 s0, s3, s18
	s_cmp_gt_i32 s0, -1
	s_cselect_b64 s[12:13], -1, 0
	s_and_b64 vcc, exec, s[12:13]
	v_lshlrev_b32_e32 v80, 1, v172
	v_mov_b32_e32 v232, 0x24210
	v_mov_b32_e32 v233, 0x24240
	v_mov_b32_e32 v234, 0x24244
	v_mov_b32_e32 v235, 0x24248
	s_barrier
	s_cbranch_vccz .LBB0_1771
	s_ashr_i32 s19, s18, 31
	s_lshl_b64 s[4:5], s[18:19], 18
	s_add_u32 s4, s14, s4
	s_addc_u32 s5, s15, s5
	s_lshl_b32 s14, s18, 6
	s_ashr_i32 s15, s14, 31
	s_lshl_b64 s[14:15], s[14:15], 1
	s_add_u32 s14, s10, s14
	s_addc_u32 s15, s11, s15
	v_lshl_add_u64 v[6:7], s[4:5], 0, v[174:175]
	v_mov_b32_e32 v81, v1
	s_waitcnt vmcnt(1)
	v_lshl_add_u64 v[10:11], s[14:15], 0, v[14:15]
	v_lshl_add_u64 v[6:7], v[6:7], 0, v[80:81]
	v_lshl_add_u64 v[10:11], v[10:11], 0, v[80:81]
	global_load_dwordx4 v[6:9], v[6:7], off offset:3072
	s_nop 0
	global_load_dwordx4 v[10:13], v[10:11], off
	s_waitcnt vmcnt(1)
	ds_write_b128 v245, v[6:9]
	s_waitcnt vmcnt(0)
	ds_write_b128 v245, v[10:13] offset:9216
